# m2 SSM second group iteration (gi=1 code copy): skip-term loads batched, scan reads batched + plain fma, same as the gi=0 copy
# speedup vs baseline: 1.0019x; 1.0000x over previous
.LBB0_493:
	s_or_b64 exec, exec, s[12:13]
	v_lshl_add_u64 v[38:39], v[130:131], 1, v[86:87]
	v_lshl_add_u64 v[42:43], v[38:39], 0, v[74:75]
	global_load_ushort v41, v[42:43], off
	v_lshl_add_u64 v[42:43], v[38:39], 0, v[98:99]
	v_lshl_add_u64 v[44:45], v[38:39], 0, v[100:101]
	global_load_ushort v42, v[42:43], off
	v_mov_b32_e32 v183, 0
	global_load_ushort v43, v[44:45], off
	v_lshl_add_u64 v[44:45], v[38:39], 0, v[102:103]
	global_load_ushort v44, v[44:45], off
	s_and_b64 vcc, exec, s[38:39]
	s_cbranch_vccnz .Lm2ub_zero
	v_lshl_add_u64 v[46:47], v[38:39], 0, v[104:105]
	global_load_ushort v184, v[46:47], off
	v_lshl_add_u64 v[46:47], v[38:39], 0, v[108:109]
	global_load_ushort v182, v[46:47], off
	v_lshl_add_u64 v[46:47], v[38:39], 0, v[112:113]
	global_load_ushort v166, v[46:47], off
	v_lshl_add_u64 v[46:47], v[38:39], 0, v[116:117]
	global_load_ushort v163, v[46:47], off
	v_lshl_add_u64 v[46:47], v[38:39], 0, v[120:121]
	global_load_ushort v148, v[46:47], off
	v_lshl_add_u64 v[46:47], v[38:39], 0, v[124:125]
	global_load_ushort v147, v[46:47], off
	v_lshl_add_u64 v[46:47], v[38:39], 0, v[106:107]
	global_load_ushort v183, v[46:47], off
	v_lshl_add_u64 v[46:47], v[38:39], 0, v[110:111]
	global_load_ushort v181, v[46:47], off
	v_lshl_add_u64 v[46:47], v[38:39], 0, v[114:115]
	global_load_ushort v164, v[46:47], off
	v_lshl_add_u64 v[46:47], v[38:39], 0, v[118:119]
	global_load_ushort v162, v[46:47], off
	v_lshl_add_u64 v[46:47], v[38:39], 0, v[122:123]
	global_load_ushort v146, v[46:47], off
	v_lshl_add_u64 v[46:47], v[38:39], 0, v[126:127]
	global_load_ushort v131, v[46:47], off
	s_waitcnt vmcnt(0)
	v_lshlrev_b32_e32 v184, 16, v184
	v_lshlrev_b32_e32 v182, 16, v182
	v_lshlrev_b32_e32 v166, 16, v166
	v_lshlrev_b32_e32 v163, 16, v163
	v_lshlrev_b32_e32 v148, 16, v148
	v_lshlrev_b32_e32 v147, 16, v147
	v_lshlrev_b32_e32 v183, 16, v183
	v_lshlrev_b32_e32 v181, 16, v181
	v_lshlrev_b32_e32 v164, 16, v164
	v_lshlrev_b32_e32 v162, 16, v162
	v_lshlrev_b32_e32 v146, 16, v146
	v_lshlrev_b32_e32 v131, 16, v131
	s_branch .LBB0_517
.Lm2ub_zero:
	v_mov_b32_e32 v184, 0
	v_mov_b32_e32 v182, 0
	v_mov_b32_e32 v166, 0
	v_mov_b32_e32 v163, 0
	v_mov_b32_e32 v148, 0
	v_mov_b32_e32 v147, 0
	v_mov_b32_e32 v183, 0
	v_mov_b32_e32 v181, 0
	v_mov_b32_e32 v164, 0
	v_mov_b32_e32 v162, 0
	v_mov_b32_e32 v146, 0
	v_mov_b32_e32 v131, 0
.LBB0_517:
	v_lshl_or_b32 v38, v40, 4, v76
	s_waitcnt vmcnt(4)
	v_mfma_f32_16x16x32_bf16 v[168:171], v[66:69], v[30:33], 0
	v_ashrrev_i32_e32 v39, 31, v38
	v_add_u32_e32 v154, v139, v130
	v_lshlrev_b64 v[38:39], 8, v[38:39]
	v_mfma_f32_16x16x32_bf16 v[172:175], v[66:69], v[34:37], 0
	v_ashrrev_i32_e32 v155, 31, v154
	v_lshl_add_u64 v[38:39], v[88:89], 0, v[38:39]
	v_lshl_add_u64 v[154:155], v[154:155], 2, s[52:53]
	v_add_u32_e32 v165, 0x400, v140
	s_waitcnt vmcnt(3)
	v_lshlrev_b32_e32 v188, 16, v41
	s_waitcnt vmcnt(2)
	v_lshlrev_b32_e32 v187, 16, v42
	s_waitcnt vmcnt(1)
	v_lshlrev_b32_e32 v186, 16, v43
	s_waitcnt vmcnt(0)
	v_lshlrev_b32_e32 v185, 16, v44
	global_load_dwordx4 v[50:53], v[38:39], off
	global_load_dwordx4 v[46:49], v[38:39], off offset:64
	global_load_dwordx4 v[42:45], v[38:39], off offset:128
	s_nop 0
	global_load_dwordx4 v[38:41], v[38:39], off offset:192
	v_cndmask_b32_e64 v129, v3, v1, s[8:9]
	global_load_dword v149, v[154:155], off
	ds_write2_b32 v140, v168, v172 offset1:16
	ds_write2_b32 v140, v169, v173 offset0:132 offset1:148
	ds_write2_b32 v165, v170, v174 offset0:8 offset1:24
	ds_write2_b32 v165, v171, v175 offset0:140 offset1:156
	v_mfma_f32_16x16x32_bf16 v[168:171], v[66:69], v[22:25], 0
	v_cndmask_b32_e64 v155, v73, v71, s[8:9]
	v_cndmask_b32_e64 v154, v72, v70, s[8:9]
	v_mov_b32_e32 v132, v129
	v_mfma_f32_16x16x32_bf16 v[172:175], v[66:69], v[26:29], 0
	s_nop 7
	ds_write2_b32 v140, v168, v172 offset0:32 offset1:48
	ds_write2_b32 v140, v169, v173 offset0:164 offset1:180
	ds_write2_b32 v165, v170, v174 offset0:40 offset1:56
	ds_write2_b32 v165, v171, v175 offset0:172 offset1:188
	v_mfma_f32_16x16x32_bf16 v[168:171], v[66:69], v[16:19], 0
	v_cndmask_b32_e64 v128, v2, v0, s[8:9]
	v_add_u32_e32 v167, 32, v141
	v_add_u32_e32 v180, 0xf0, v141
	v_mfma_f32_16x16x32_bf16 v[172:175], v[66:69], v[12:15], 0
	s_nop 7
	ds_write2_b32 v140, v168, v172 offset0:64 offset1:80
	ds_write2_b32 v140, v169, v173 offset0:196 offset1:212
	ds_write2_b32 v165, v170, v174 offset0:72 offset1:88
	ds_write2_b32 v165, v171, v175 offset0:204 offset1:220
	v_mfma_f32_16x16x32_bf16 v[168:171], v[66:69], v[8:11], 0
	v_lshl_add_u32 v130, v130, 1, v143
	s_and_b64 vcc, exec, s[38:39]
	v_mfma_f32_16x16x32_bf16 v[66:69], v[66:69], v[4:7], 0
	s_nop 7
	ds_write2_b32 v140, v168, v66 offset0:96 offset1:112
	ds_write2_b32 v140, v169, v67 offset0:228 offset1:244
	ds_write2_b32 v165, v170, v68 offset0:104 offset1:120
	ds_write2_b32 v165, v171, v69 offset0:236 offset1:252
	s_waitcnt lgkmcnt(0)
	ds_read2st64_b32 v[216:217], v141 offset1:1
	v_add_u32_e32 v207, 16, v141
	ds_read2st64_b32 v[218:219], v207 offset0:2 offset1:3
	v_add_u32_e32 v207, 32, v141
	ds_read2st64_b32 v[220:221], v207 offset0:4 offset1:5
	v_add_u32_e32 v207, 48, v141
	ds_read2st64_b32 v[222:223], v207 offset0:6 offset1:7
	v_add_u32_e32 v207, 64, v141
	ds_read2st64_b32 v[224:225], v207 offset0:8 offset1:9
	v_add_u32_e32 v207, 80, v141
	ds_read2st64_b32 v[226:227], v207 offset0:10 offset1:11
	v_add_u32_e32 v207, 96, v141
	ds_read2st64_b32 v[228:229], v207 offset0:12 offset1:13
	v_add_u32_e32 v207, 112, v141
	ds_read2st64_b32 v[230:231], v207 offset0:14 offset1:15
	v_add_u32_e32 v207, 128, v141
	ds_read2st64_b32 v[232:233], v207 offset0:16 offset1:17
	v_add_u32_e32 v207, 144, v141
	ds_read2st64_b32 v[234:235], v207 offset0:18 offset1:19
	v_add_u32_e32 v207, 160, v141
	ds_read2st64_b32 v[236:237], v207 offset0:20 offset1:21
	v_add_u32_e32 v207, 176, v141
	ds_read2st64_b32 v[238:239], v207 offset0:22 offset1:23
	v_add_u32_e32 v207, 192, v141
	ds_read2st64_b32 v[240:241], v207 offset0:24 offset1:25
	v_add_u32_e32 v207, 208, v141
	ds_read2st64_b32 v[242:243], v207 offset0:26 offset1:27
	v_add_u32_e32 v207, 224, v141
	ds_read2st64_b32 v[244:245], v207 offset0:28 offset1:29
	v_add_u32_e32 v207, 240, v141
	ds_read2st64_b32 v[246:247], v207 offset0:30 offset1:31
	s_waitcnt lgkmcnt(15)
	v_fma_f32 v216, v128, v154, v216
	v_fma_f32 v217, v128, v155, v217
	v_fma_f32 v216, -v132, v155, v216
	v_fma_f32 v217, v132, v154, v217
	v_mov_b32_e32 v154, v216
	v_mov_b32_e32 v155, v217
	v_mov_b32_e32 v66, v128
	v_cvt_pk_bf16_f32 v156, v154, v155
	ds_write_b16 v142, v156
	ds_write_b16_d16_hi v142, v156 offset:128
	s_waitcnt lgkmcnt(15)
	v_fma_f32 v218, v128, v154, v218
	v_fma_f32 v219, v128, v155, v219
	v_fma_f32 v218, -v132, v155, v218
	v_fma_f32 v219, v132, v154, v219
	v_mov_b32_e32 v154, v218
	v_mov_b32_e32 v155, v219
	v_mov_b32_e32 v67, v128
	v_cvt_pk_bf16_f32 v156, v154, v155
	ds_write_b16 v142, v156 offset:272
	ds_write_b16_d16_hi v142, v156 offset:400
	s_waitcnt lgkmcnt(15)
	v_fma_f32 v220, v128, v154, v220
	v_fma_f32 v221, v128, v155, v221
	v_fma_f32 v220, -v132, v155, v220
	v_fma_f32 v221, v132, v154, v221
	v_mov_b32_e32 v154, v220
	v_mov_b32_e32 v155, v221
	v_add_u32_e32 v168, 48, v141
	v_cvt_pk_bf16_f32 v156, v154, v155
	ds_write_b16 v142, v156 offset:544
	ds_write_b16_d16_hi v142, v156 offset:672
	s_waitcnt lgkmcnt(15)
	v_fma_f32 v222, v128, v154, v222
	v_fma_f32 v223, v128, v155, v223
	v_fma_f32 v222, -v132, v155, v222
	v_fma_f32 v223, v132, v154, v223
	v_mov_b32_e32 v154, v222
	v_mov_b32_e32 v155, v223
	v_add_u32_e32 v169, 64, v141
	v_cvt_pk_bf16_f32 v156, v154, v155
	ds_write_b16 v142, v156 offset:816
	ds_write_b16_d16_hi v142, v156 offset:944
	s_waitcnt lgkmcnt(15)
	v_fma_f32 v224, v128, v154, v224
	v_fma_f32 v225, v128, v155, v225
	v_fma_f32 v224, -v132, v155, v224
	v_fma_f32 v225, v132, v154, v225
	v_mov_b32_e32 v154, v224
	v_mov_b32_e32 v155, v225
	v_add_u32_e32 v170, 0x50, v141
	v_cvt_pk_bf16_f32 v156, v154, v155
	ds_write_b16 v142, v156 offset:1088
	ds_write_b16_d16_hi v142, v156 offset:1216
	s_waitcnt lgkmcnt(15)
	v_fma_f32 v226, v128, v154, v226
	v_fma_f32 v227, v128, v155, v227
	v_fma_f32 v226, -v132, v155, v226
	v_fma_f32 v227, v132, v154, v227
	v_mov_b32_e32 v154, v226
	v_mov_b32_e32 v155, v227
	v_add_u32_e32 v171, 0x60, v141
	v_cvt_pk_bf16_f32 v156, v154, v155
	ds_write_b16 v142, v156 offset:1360
	ds_write_b16_d16_hi v142, v156 offset:1488
	s_waitcnt lgkmcnt(15)
	v_fma_f32 v228, v128, v154, v228
	v_fma_f32 v229, v128, v155, v229
	v_fma_f32 v228, -v132, v155, v228
	v_fma_f32 v229, v132, v154, v229
	v_mov_b32_e32 v154, v228
	v_mov_b32_e32 v155, v229
	v_add_u32_e32 v172, 0x70, v141
	v_cvt_pk_bf16_f32 v156, v154, v155
	ds_write_b16 v142, v156 offset:1632
	ds_write_b16_d16_hi v142, v156 offset:1760
	s_waitcnt lgkmcnt(15)
	v_fma_f32 v230, v128, v154, v230
	v_fma_f32 v231, v128, v155, v231
	v_fma_f32 v230, -v132, v155, v230
	v_fma_f32 v231, v132, v154, v231
	v_mov_b32_e32 v154, v230
	v_mov_b32_e32 v155, v231
	v_add_u32_e32 v173, 0x80, v141
	v_cvt_pk_bf16_f32 v156, v154, v155
	ds_write_b16 v142, v156 offset:1904
	ds_write_b16_d16_hi v142, v156 offset:2032
	s_waitcnt lgkmcnt(15)
	v_fma_f32 v232, v128, v154, v232
	v_fma_f32 v233, v128, v155, v233
	v_fma_f32 v232, -v132, v155, v232
	v_fma_f32 v233, v132, v154, v233
	v_mov_b32_e32 v154, v232
	v_mov_b32_e32 v155, v233
	v_add_u32_e32 v174, 0x90, v141
	v_cvt_pk_bf16_f32 v156, v154, v155
	ds_write_b16 v142, v156 offset:2176
	ds_write_b16_d16_hi v142, v156 offset:2304
	s_waitcnt lgkmcnt(15)
	v_fma_f32 v234, v128, v154, v234
	v_fma_f32 v235, v128, v155, v235
	v_fma_f32 v234, -v132, v155, v234
	v_fma_f32 v235, v132, v154, v235
	v_mov_b32_e32 v154, v234
	v_mov_b32_e32 v155, v235
	v_add_u32_e32 v175, 0xa0, v141
	v_cvt_pk_bf16_f32 v156, v154, v155
	ds_write_b16 v142, v156 offset:2448
	ds_write_b16_d16_hi v142, v156 offset:2576
	s_waitcnt lgkmcnt(15)
	v_fma_f32 v236, v128, v154, v236
	v_fma_f32 v237, v128, v155, v237
	v_fma_f32 v236, -v132, v155, v236
	v_fma_f32 v237, v132, v154, v237
	v_mov_b32_e32 v154, v236
	v_mov_b32_e32 v155, v237
	v_add_u32_e32 v176, 0xb0, v141
	v_cvt_pk_bf16_f32 v156, v154, v155
	ds_write_b16 v142, v156 offset:2720
	ds_write_b16_d16_hi v142, v156 offset:2848
	s_waitcnt lgkmcnt(15)
	v_fma_f32 v238, v128, v154, v238
	v_fma_f32 v239, v128, v155, v239
	v_fma_f32 v238, -v132, v155, v238
	v_fma_f32 v239, v132, v154, v239
	v_mov_b32_e32 v154, v238
	v_mov_b32_e32 v155, v239
	v_add_u32_e32 v177, 0xc0, v141
	v_cvt_pk_bf16_f32 v156, v154, v155
	ds_write_b16 v142, v156 offset:2992
	ds_write_b16_d16_hi v142, v156 offset:3120
	s_waitcnt lgkmcnt(15)
	v_fma_f32 v240, v128, v154, v240
	v_fma_f32 v241, v128, v155, v241
	v_fma_f32 v240, -v132, v155, v240
	v_fma_f32 v241, v132, v154, v241
	v_mov_b32_e32 v154, v240
	v_mov_b32_e32 v155, v241
	v_add_u32_e32 v178, 0xd0, v141
	v_cvt_pk_bf16_f32 v156, v154, v155
	ds_write_b16 v142, v156 offset:3264
	ds_write_b16_d16_hi v142, v156 offset:3392
	s_waitcnt lgkmcnt(15)
	v_fma_f32 v242, v128, v154, v242
	v_fma_f32 v243, v128, v155, v243
	v_fma_f32 v242, -v132, v155, v242
	v_fma_f32 v243, v132, v154, v243
	v_mov_b32_e32 v154, v242
	v_mov_b32_e32 v155, v243
	v_add_u32_e32 v179, 0xe0, v141
	v_cvt_pk_bf16_f32 v156, v154, v155
	ds_write_b16 v142, v156 offset:3536
	ds_write_b16_d16_hi v142, v156 offset:3664
	s_waitcnt lgkmcnt(15)
	v_fma_f32 v244, v128, v154, v244
	v_fma_f32 v245, v128, v155, v245
	v_fma_f32 v244, -v132, v155, v244
	v_fma_f32 v245, v132, v154, v245
	v_mov_b32_e32 v154, v244
	v_mov_b32_e32 v155, v245
	v_mov_b32_e32 v68, v129
	v_cvt_pk_bf16_f32 v156, v154, v155
	ds_write_b16 v142, v156 offset:3808
	ds_write_b16_d16_hi v142, v156 offset:3936
	v_mov_b32_e32 v69, v129
	s_waitcnt lgkmcnt(15)
	v_fma_f32 v246, v128, v154, v246
	v_fma_f32 v247, v128, v155, v247
	v_fma_f32 v246, -v132, v155, v246
	v_fma_f32 v247, v132, v154, v247
	v_mov_b32_e32 v128, v246
	v_mov_b32_e32 v129, v247
	s_nop 0
	v_cvt_pk_bf16_f32 v132, v128, v129
	ds_write_b16 v142, v132 offset:4080
	ds_write_b16_d16_hi v142, v132 offset:4208
	s_waitcnt lgkmcnt(0)
	ds_read_b128 v[208:211], v144
	ds_read_b128 v[212:215], v144 offset:64
	s_waitcnt vmcnt(4) lgkmcnt(1)
	v_mfma_f32_16x16x32_bf16 v[208:211], v[208:211], v[50:53], 0
	s_waitcnt vmcnt(3) lgkmcnt(0)
	v_mfma_f32_16x16x32_bf16 v[208:211], v[212:215], v[46:49], v[208:211]
	ds_read_b128 v[212:215], v144 offset:128
	s_waitcnt vmcnt(2) lgkmcnt(0)
	v_mfma_f32_16x16x32_bf16 v[208:211], v[212:215], v[42:45], v[208:211]
	ds_read_b128 v[212:215], v144 offset:192
	s_waitcnt vmcnt(1) lgkmcnt(0)
	v_mfma_f32_16x16x32_bf16 v[208:211], v[212:215], v[38:41], v[208:211]
	s_waitcnt vmcnt(0)
	s_nop 6
	v_fma_f32 v132, v149, v188, v208
	v_mul_f32_e32 v154, 0x3d372713, v132
	v_mul_f32_e32 v154, v132, v154
	v_fma_f32 v154, v132, v154, v132
	v_mul_f32_e32 v154, 0xbfcc422a, v154
	v_mul_f32_e32 v154, 0x3fb8aa3b, v154
	v_exp_f32_e32 v154, v154
	v_fmac_f32_e32 v211, v149, v185
	v_add_f32_e32 v154, 1.0, v154
	v_rcp_f32_e32 v154, v154
	s_nop 0
	v_mul_f32_e32 v132, v132, v154
	v_cvt_pk_bf16_f32 v132, v132, v20
	ds_write_b16 v130, v132
	v_fma_f32 v132, v149, v187, v209
	v_mul_f32_e32 v154, 0x3d372713, v132
	v_mul_f32_e32 v154, v132, v154
	v_fma_f32 v154, v132, v154, v132
	v_mul_f32_e32 v154, 0xbfcc422a, v154
	v_mul_f32_e32 v154, 0x3fb8aa3b, v154
	v_exp_f32_e32 v154, v154
	s_nop 0
	v_add_f32_e32 v154, 1.0, v154
	v_rcp_f32_e32 v154, v154
	s_nop 0
	v_mul_f32_e32 v132, v132, v154
	v_cvt_pk_bf16_f32 v132, v132, v20
	ds_write_b16 v130, v132 offset:528
	v_fma_f32 v132, v149, v186, v210
	v_mul_f32_e32 v154, 0x3d372713, v132
	v_mul_f32_e32 v154, v132, v154
	v_fma_f32 v154, v132, v154, v132
	v_mul_f32_e32 v154, 0xbfcc422a, v154
	v_mul_f32_e32 v154, 0x3fb8aa3b, v154
	v_exp_f32_e32 v154, v154
	s_nop 0
	v_add_f32_e32 v154, 1.0, v154
	v_rcp_f32_e32 v154, v154
	s_nop 0
	v_mul_f32_e32 v132, v132, v154
	v_cvt_pk_bf16_f32 v132, v132, v20
	ds_write_b16 v130, v132 offset:1056
	v_mul_f32_e32 v132, 0x3d372713, v211
	v_mul_f32_e32 v132, v211, v132
	v_fma_f32 v132, v211, v132, v211
	v_mul_f32_e32 v132, 0xbfcc422a, v132
	v_mul_f32_e32 v132, 0x3fb8aa3b, v132
	v_exp_f32_e32 v132, v132
	s_nop 0
	v_add_f32_e32 v132, 1.0, v132
	v_rcp_f32_e32 v132, v132
	s_nop 0
	v_mul_f32_e32 v132, v211, v132
	v_cvt_pk_bf16_f32 v132, v132, v20
	ds_write_b16 v130, v132 offset:1584
	s_waitcnt lgkmcnt(0)
	s_cbranch_vccnz .LBB0_521
	v_mfma_f32_16x16x32_bf16 v[186:189], v[62:65], v[30:33], 0
	v_mfma_f32_16x16x32_bf16 v[208:211], v[62:65], v[34:37], 0
	s_nop 7
	ds_write2_b32 v140, v186, v208 offset1:16
	ds_write2_b32 v140, v187, v209 offset0:132 offset1:148
	ds_write2_b32 v165, v188, v210 offset0:8 offset1:24
	ds_write2_b32 v165, v189, v211 offset0:140 offset1:156
	v_mfma_f32_16x16x32_bf16 v[186:189], v[62:65], v[22:25], 0
	v_mfma_f32_16x16x32_bf16 v[208:211], v[62:65], v[26:29], 0
	s_nop 7
	ds_write2_b32 v140, v186, v208 offset0:32 offset1:48
	ds_write2_b32 v140, v187, v209 offset0:164 offset1:180
	ds_write2_b32 v165, v188, v210 offset0:40 offset1:56
	ds_write2_b32 v165, v189, v211 offset0:172 offset1:188
	v_mfma_f32_16x16x32_bf16 v[186:189], v[62:65], v[16:19], 0
	v_mfma_f32_16x16x32_bf16 v[208:211], v[62:65], v[12:15], 0
	s_nop 7
	ds_write2_b32 v140, v186, v208 offset0:64 offset1:80
	ds_write2_b32 v140, v187, v209 offset0:196 offset1:212
	ds_write2_b32 v165, v188, v210 offset0:72 offset1:88
	ds_write2_b32 v165, v189, v211 offset0:204 offset1:220
	v_mfma_f32_16x16x32_bf16 v[186:189], v[62:65], v[8:11], 0
	v_mfma_f32_16x16x32_bf16 v[62:65], v[62:65], v[4:7], 0
	s_nop 7
	ds_write2_b32 v140, v186, v62 offset0:96 offset1:112
	ds_write2_b32 v140, v187, v63 offset0:228 offset1:244
	ds_write2_b32 v165, v188, v64 offset0:104 offset1:120
	ds_write2_b32 v165, v189, v65 offset0:236 offset1:252
	s_waitcnt lgkmcnt(0)
	ds_read2st64_b32 v[216:217], v141 offset1:1
	v_add_u32_e32 v207, 16, v141
	ds_read2st64_b32 v[218:219], v207 offset0:2 offset1:3
	v_add_u32_e32 v207, 32, v141
	ds_read2st64_b32 v[220:221], v207 offset0:4 offset1:5
	v_add_u32_e32 v207, 48, v141
	ds_read2st64_b32 v[222:223], v207 offset0:6 offset1:7
	v_add_u32_e32 v207, 64, v141
	ds_read2st64_b32 v[224:225], v207 offset0:8 offset1:9
	v_add_u32_e32 v207, 80, v141
	ds_read2st64_b32 v[226:227], v207 offset0:10 offset1:11
	v_add_u32_e32 v207, 96, v141
	ds_read2st64_b32 v[228:229], v207 offset0:12 offset1:13
	v_add_u32_e32 v207, 112, v141
	ds_read2st64_b32 v[230:231], v207 offset0:14 offset1:15
	v_add_u32_e32 v207, 128, v141
	ds_read2st64_b32 v[232:233], v207 offset0:16 offset1:17
	v_add_u32_e32 v207, 144, v141
	ds_read2st64_b32 v[234:235], v207 offset0:18 offset1:19
	v_add_u32_e32 v207, 160, v141
	ds_read2st64_b32 v[236:237], v207 offset0:20 offset1:21
	v_add_u32_e32 v207, 176, v141
	ds_read2st64_b32 v[238:239], v207 offset0:22 offset1:23
	v_add_u32_e32 v207, 192, v141
	ds_read2st64_b32 v[240:241], v207 offset0:24 offset1:25
	v_add_u32_e32 v207, 208, v141
	ds_read2st64_b32 v[242:243], v207 offset0:26 offset1:27
	v_add_u32_e32 v207, 224, v141
	ds_read2st64_b32 v[244:245], v207 offset0:28 offset1:29
	v_add_u32_e32 v207, 240, v141
	ds_read2st64_b32 v[246:247], v207 offset0:30 offset1:31
	s_nop 0
	s_nop 0
	s_waitcnt lgkmcnt(15)
	v_fma_f32 v216, v66, v128, v216
	v_fma_f32 v217, v67, v129, v217
	v_fma_f32 v216, -v69, v129, v216
	v_fma_f32 v217, v68, v128, v217
	v_mov_b32_e32 v62, v216
	v_mov_b32_e32 v63, v217
	s_nop 0
	v_cvt_pk_bf16_f32 v64, v62, v63
	ds_write_b16 v142, v64
	ds_write_b16_d16_hi v142, v64 offset:128
	s_nop 0
	s_nop 0
	s_waitcnt lgkmcnt(15)
	v_fma_f32 v218, v66, v62, v218
	v_fma_f32 v219, v67, v63, v219
	v_fma_f32 v218, -v69, v63, v218
	v_fma_f32 v219, v68, v62, v219
	v_mov_b32_e32 v62, v218
	v_mov_b32_e32 v63, v219
	s_nop 0
	v_cvt_pk_bf16_f32 v64, v62, v63
	ds_write_b16 v142, v64 offset:272
	ds_write_b16_d16_hi v142, v64 offset:400
	s_nop 0
	s_nop 0
	s_waitcnt lgkmcnt(15)
	v_fma_f32 v220, v66, v62, v220
	v_fma_f32 v221, v67, v63, v221
	v_fma_f32 v220, -v69, v63, v220
	v_fma_f32 v221, v68, v62, v221
	v_mov_b32_e32 v62, v220
	v_mov_b32_e32 v63, v221
	s_nop 0
	v_cvt_pk_bf16_f32 v64, v62, v63
	ds_write_b16 v142, v64 offset:544
	ds_write_b16_d16_hi v142, v64 offset:672
	s_nop 0
	s_nop 0
	s_waitcnt lgkmcnt(15)
	v_fma_f32 v222, v66, v62, v222
	v_fma_f32 v223, v67, v63, v223
	v_fma_f32 v222, -v69, v63, v222
	v_fma_f32 v223, v68, v62, v223
	v_mov_b32_e32 v62, v222
	v_mov_b32_e32 v63, v223
	s_nop 0
	v_cvt_pk_bf16_f32 v64, v62, v63
	ds_write_b16 v142, v64 offset:816
	ds_write_b16_d16_hi v142, v64 offset:944
	s_nop 0
	s_nop 0
	s_waitcnt lgkmcnt(15)
	v_fma_f32 v224, v66, v62, v224
	v_fma_f32 v225, v67, v63, v225
	v_fma_f32 v224, -v69, v63, v224
	v_fma_f32 v225, v68, v62, v225
	v_mov_b32_e32 v62, v224
	v_mov_b32_e32 v63, v225
	s_nop 0
	v_cvt_pk_bf16_f32 v64, v62, v63
	ds_write_b16 v142, v64 offset:1088
	ds_write_b16_d16_hi v142, v64 offset:1216
	s_nop 0
	s_nop 0
	s_waitcnt lgkmcnt(15)
	v_fma_f32 v226, v66, v62, v226
	v_fma_f32 v227, v67, v63, v227
	v_fma_f32 v226, -v69, v63, v226
	v_fma_f32 v227, v68, v62, v227
	v_mov_b32_e32 v62, v226
	v_mov_b32_e32 v63, v227
	s_nop 0
	v_cvt_pk_bf16_f32 v64, v62, v63
	ds_write_b16 v142, v64 offset:1360
	ds_write_b16_d16_hi v142, v64 offset:1488
	s_nop 0
	s_nop 0
	s_waitcnt lgkmcnt(15)
	v_fma_f32 v228, v66, v62, v228
	v_fma_f32 v229, v67, v63, v229
	v_fma_f32 v228, -v69, v63, v228
	v_fma_f32 v229, v68, v62, v229
	v_mov_b32_e32 v62, v228
	v_mov_b32_e32 v63, v229
	s_nop 0
	v_cvt_pk_bf16_f32 v64, v62, v63
	ds_write_b16 v142, v64 offset:1632
	ds_write_b16_d16_hi v142, v64 offset:1760
	s_nop 0
	s_nop 0
	s_waitcnt lgkmcnt(15)
	v_fma_f32 v230, v66, v62, v230
	v_fma_f32 v231, v67, v63, v231
	v_fma_f32 v230, -v69, v63, v230
	v_fma_f32 v231, v68, v62, v231
	v_mov_b32_e32 v62, v230
	v_mov_b32_e32 v63, v231
	s_nop 0
	v_cvt_pk_bf16_f32 v64, v62, v63
	ds_write_b16 v142, v64 offset:1904
	ds_write_b16_d16_hi v142, v64 offset:2032
	s_nop 0
	s_nop 0
	s_waitcnt lgkmcnt(15)
	v_fma_f32 v232, v66, v62, v232
	v_fma_f32 v233, v67, v63, v233
	v_fma_f32 v232, -v69, v63, v232
	v_fma_f32 v233, v68, v62, v233
	v_mov_b32_e32 v62, v232
	v_mov_b32_e32 v63, v233
	s_nop 0
	v_cvt_pk_bf16_f32 v64, v62, v63
	ds_write_b16 v142, v64 offset:2176
	ds_write_b16_d16_hi v142, v64 offset:2304
	s_nop 0
	s_nop 0
	s_waitcnt lgkmcnt(15)
	v_fma_f32 v234, v66, v62, v234
	v_fma_f32 v235, v67, v63, v235
	v_fma_f32 v234, -v69, v63, v234
	v_fma_f32 v235, v68, v62, v235
	v_mov_b32_e32 v62, v234
	v_mov_b32_e32 v63, v235
	s_nop 0
	v_cvt_pk_bf16_f32 v64, v62, v63
	ds_write_b16 v142, v64 offset:2448
	ds_write_b16_d16_hi v142, v64 offset:2576
	s_nop 0
	s_nop 0
	s_waitcnt lgkmcnt(15)
	v_fma_f32 v236, v66, v62, v236
	v_fma_f32 v237, v67, v63, v237
	v_fma_f32 v236, -v69, v63, v236
	v_fma_f32 v237, v68, v62, v237
	v_mov_b32_e32 v62, v236
	v_mov_b32_e32 v63, v237
	s_nop 0
	v_cvt_pk_bf16_f32 v64, v62, v63
	ds_write_b16 v142, v64 offset:2720
	ds_write_b16_d16_hi v142, v64 offset:2848
	s_nop 0
	s_nop 0
	s_waitcnt lgkmcnt(15)
	v_fma_f32 v238, v66, v62, v238
	v_fma_f32 v239, v67, v63, v239
	v_fma_f32 v238, -v69, v63, v238
	v_fma_f32 v239, v68, v62, v239
	v_mov_b32_e32 v62, v238
	v_mov_b32_e32 v63, v239
	s_nop 0
	v_cvt_pk_bf16_f32 v64, v62, v63
	ds_write_b16 v142, v64 offset:2992
	ds_write_b16_d16_hi v142, v64 offset:3120
	s_nop 0
	s_nop 0
	s_waitcnt lgkmcnt(15)
	v_fma_f32 v240, v66, v62, v240
	v_fma_f32 v241, v67, v63, v241
	v_fma_f32 v240, -v69, v63, v240
	v_fma_f32 v241, v68, v62, v241
	v_mov_b32_e32 v62, v240
	v_mov_b32_e32 v63, v241
	s_nop 0
	v_cvt_pk_bf16_f32 v64, v62, v63
	ds_write_b16 v142, v64 offset:3264
	ds_write_b16_d16_hi v142, v64 offset:3392
	s_nop 0
	s_nop 0
	s_waitcnt lgkmcnt(15)
	v_fma_f32 v242, v66, v62, v242
	v_fma_f32 v243, v67, v63, v243
	v_fma_f32 v242, -v69, v63, v242
	v_fma_f32 v243, v68, v62, v243
	v_mov_b32_e32 v62, v242
	v_mov_b32_e32 v63, v243
	s_nop 0
	v_cvt_pk_bf16_f32 v64, v62, v63
	ds_write_b16 v142, v64 offset:3536
	ds_write_b16_d16_hi v142, v64 offset:3664
	s_nop 0
	s_nop 0
	s_waitcnt lgkmcnt(15)
	v_fma_f32 v244, v66, v62, v244
	v_fma_f32 v245, v67, v63, v245
	v_fma_f32 v244, -v69, v63, v244
	v_fma_f32 v245, v68, v62, v245
	v_mov_b32_e32 v62, v244
	v_mov_b32_e32 v63, v245
	s_nop 0
	v_cvt_pk_bf16_f32 v64, v62, v63
	ds_write_b16 v142, v64 offset:3808
	ds_write_b16_d16_hi v142, v64 offset:3936
	s_nop 0
	s_nop 0
	s_waitcnt lgkmcnt(15)
	v_fma_f32 v246, v66, v62, v246
	v_fma_f32 v247, v67, v63, v247
	v_fma_f32 v246, -v69, v63, v246
	v_fma_f32 v247, v68, v62, v247
	v_mov_b32_e32 v128, v246
	v_mov_b32_e32 v129, v247
	s_nop 0
	v_cvt_pk_bf16_f32 v62, v128, v129
	ds_write_b16 v142, v62 offset:4080
	ds_write_b16_d16_hi v142, v62 offset:4208
	s_waitcnt lgkmcnt(0)
	ds_read_b128 v[62:65], v144
	ds_read_b128 v[186:189], v144 offset:64
	s_waitcnt lgkmcnt(1)
	v_mfma_f32_16x16x32_bf16 v[62:65], v[62:65], v[50:53], 0
	s_waitcnt lgkmcnt(0)
	v_mfma_f32_16x16x32_bf16 v[62:65], v[186:189], v[46:49], v[62:65]
	ds_read_b128 v[186:189], v144 offset:128
	s_waitcnt lgkmcnt(0)
	v_mfma_f32_16x16x32_bf16 v[62:65], v[186:189], v[42:45], v[62:65]
	ds_read_b128 v[186:189], v144 offset:192
	s_waitcnt lgkmcnt(0)
	v_mfma_f32_16x16x32_bf16 v[62:65], v[186:189], v[38:41], v[62:65]
	s_nop 7
	v_fma_f32 v62, v184, v149, v62
	v_mul_f32_e32 v132, 0x3d372713, v62
	v_mul_f32_e32 v132, v62, v132
	v_fma_f32 v132, v62, v132, v62
	v_mul_f32_e32 v132, 0xbfcc422a, v132
	v_mul_f32_e32 v132, 0x3fb8aa3b, v132
	v_exp_f32_e32 v132, v132
	v_fmac_f32_e32 v65, v181, v149
	v_add_f32_e32 v132, 1.0, v132
	v_rcp_f32_e32 v132, v132
	s_nop 0
	v_mul_f32_e32 v62, v62, v132
	v_cvt_pk_bf16_f32 v62, v62, v20
	ds_write_b16 v130, v62 offset:8448
	v_fma_f32 v62, v183, v149, v63
	v_mul_f32_e32 v63, 0x3d372713, v62
	v_mul_f32_e32 v63, v62, v63
	v_fma_f32 v63, v62, v63, v62
	v_mul_f32_e32 v63, 0xbfcc422a, v63
	v_mul_f32_e32 v63, 0x3fb8aa3b, v63
	v_exp_f32_e32 v63, v63
	s_nop 0
	v_add_f32_e32 v63, 1.0, v63
	v_rcp_f32_e32 v63, v63
	s_nop 0
	v_mul_f32_e32 v62, v62, v63
	v_cvt_pk_bf16_f32 v62, v62, v20
	ds_write_b16 v130, v62 offset:8976
	v_fma_f32 v62, v182, v149, v64
	v_mul_f32_e32 v63, 0x3d372713, v62
	v_mul_f32_e32 v63, v62, v63
	v_fma_f32 v63, v62, v63, v62
	v_mul_f32_e32 v63, 0xbfcc422a, v63
	v_mul_f32_e32 v63, 0x3fb8aa3b, v63
	v_exp_f32_e32 v63, v63
	s_nop 0
	v_add_f32_e32 v63, 1.0, v63
	v_rcp_f32_e32 v63, v63
	s_nop 0
	v_mul_f32_e32 v62, v62, v63
	v_cvt_pk_bf16_f32 v62, v62, v20
	ds_write_b16 v130, v62 offset:9504
	v_mul_f32_e32 v62, 0x3d372713, v65
	v_mul_f32_e32 v62, v65, v62
	v_fma_f32 v62, v65, v62, v65
	v_mul_f32_e32 v62, 0xbfcc422a, v62
	v_mul_f32_e32 v62, 0x3fb8aa3b, v62
	v_exp_f32_e32 v62, v62
	s_nop 0
	v_add_f32_e32 v62, 1.0, v62
	v_rcp_f32_e32 v62, v62
	s_nop 0
	v_mul_f32_e32 v62, v65, v62
	v_cvt_pk_bf16_f32 v62, v62, v20
	ds_write_b16 v130, v62 offset:10032
	s_waitcnt lgkmcnt(0)
	s_and_b64 vcc, exec, s[38:39]
	s_cbranch_vccz .LBB0_522

.LBB0_520:
	v_mfma_f32_16x16x32_bf16 v[30:33], v[54:57], v[30:33], 0
	v_mfma_f32_16x16x32_bf16 v[34:37], v[54:57], v[34:37], 0
	s_nop 7
	ds_write2_b32 v140, v30, v34 offset1:16
	ds_write2_b32 v140, v31, v35 offset0:132 offset1:148
	ds_write2_b32 v165, v32, v36 offset0:8 offset1:24
	v_mfma_f32_16x16x32_bf16 v[22:25], v[54:57], v[22:25], 0
	v_mfma_f32_16x16x32_bf16 v[26:29], v[54:57], v[26:29], 0
	ds_write2_b32 v165, v33, v37 offset0:140 offset1:156
	s_nop 6
	ds_write2_b32 v140, v22, v26 offset0:32 offset1:48
	ds_write2_b32 v140, v23, v27 offset0:164 offset1:180
	v_mfma_f32_16x16x32_bf16 v[16:19], v[54:57], v[16:19], 0
	v_mfma_f32_16x16x32_bf16 v[12:15], v[54:57], v[12:15], 0
	ds_write2_b32 v165, v24, v28 offset0:40 offset1:56
	ds_write2_b32 v165, v25, v29 offset0:172 offset1:188
	s_nop 5
	ds_write2_b32 v140, v16, v12 offset0:64 offset1:80
	ds_write2_b32 v140, v17, v13 offset0:196 offset1:212
	ds_write2_b32 v165, v18, v14 offset0:72 offset1:88
	ds_write2_b32 v165, v19, v15 offset0:204 offset1:220
	v_mfma_f32_16x16x32_bf16 v[8:11], v[54:57], v[8:11], 0
	v_mfma_f32_16x16x32_bf16 v[4:7], v[54:57], v[4:7], 0
	s_nop 7
	ds_write2_b32 v140, v8, v4 offset0:96 offset1:112
	ds_write2_b32 v140, v9, v5 offset0:228 offset1:244
	ds_write2_b32 v165, v10, v6 offset0:104 offset1:120
	ds_write2_b32 v165, v11, v7 offset0:236 offset1:252
	s_waitcnt lgkmcnt(0)
	ds_read2st64_b32 v[216:217], v141 offset1:1
	v_add_u32_e32 v207, 16, v141
	ds_read2st64_b32 v[218:219], v207 offset0:2 offset1:3
	v_add_u32_e32 v207, 32, v141
	ds_read2st64_b32 v[220:221], v207 offset0:4 offset1:5
	v_add_u32_e32 v207, 48, v141
	ds_read2st64_b32 v[222:223], v207 offset0:6 offset1:7
	v_add_u32_e32 v207, 64, v141
	ds_read2st64_b32 v[224:225], v207 offset0:8 offset1:9
	v_add_u32_e32 v207, 80, v141
	ds_read2st64_b32 v[226:227], v207 offset0:10 offset1:11
	v_add_u32_e32 v207, 96, v141
	ds_read2st64_b32 v[228:229], v207 offset0:12 offset1:13
	v_add_u32_e32 v207, 112, v141
	ds_read2st64_b32 v[230:231], v207 offset0:14 offset1:15
	v_add_u32_e32 v207, 128, v141
	ds_read2st64_b32 v[232:233], v207 offset0:16 offset1:17
	v_add_u32_e32 v207, 144, v141
	ds_read2st64_b32 v[234:235], v207 offset0:18 offset1:19
	v_add_u32_e32 v207, 160, v141
	ds_read2st64_b32 v[236:237], v207 offset0:20 offset1:21
	v_add_u32_e32 v207, 176, v141
	ds_read2st64_b32 v[238:239], v207 offset0:22 offset1:23
	v_add_u32_e32 v207, 192, v141
	ds_read2st64_b32 v[240:241], v207 offset0:24 offset1:25
	v_add_u32_e32 v207, 208, v141
	ds_read2st64_b32 v[242:243], v207 offset0:26 offset1:27
	v_add_u32_e32 v207, 224, v141
	ds_read2st64_b32 v[244:245], v207 offset0:28 offset1:29
	v_add_u32_e32 v207, 240, v141
	ds_read2st64_b32 v[246:247], v207 offset0:30 offset1:31
	s_nop 0
	s_nop 0
	s_waitcnt lgkmcnt(15)
	v_fma_f32 v216, v66, v128, v216
	v_fma_f32 v217, v67, v129, v217
	v_fma_f32 v216, -v69, v129, v216
	v_fma_f32 v217, v68, v128, v217
	v_mov_b32_e32 v4, v216
	v_mov_b32_e32 v5, v217
	s_nop 0
	v_cvt_pk_bf16_f32 v6, v4, v5
	ds_write_b16 v142, v6
	ds_write_b16_d16_hi v142, v6 offset:128
	s_nop 0
	s_nop 0
	s_waitcnt lgkmcnt(15)
	v_fma_f32 v218, v66, v4, v218
	v_fma_f32 v219, v67, v5, v219
	v_fma_f32 v218, -v69, v5, v218
	v_fma_f32 v219, v68, v4, v219
	v_mov_b32_e32 v4, v218
	v_mov_b32_e32 v5, v219
	s_nop 0
	v_cvt_pk_bf16_f32 v6, v4, v5
	ds_write_b16 v142, v6 offset:272
	ds_write_b16_d16_hi v142, v6 offset:400
	s_nop 0
	s_nop 0
	s_waitcnt lgkmcnt(15)
	v_fma_f32 v220, v66, v4, v220
	v_fma_f32 v221, v67, v5, v221
	v_fma_f32 v220, -v69, v5, v220
	v_fma_f32 v221, v68, v4, v221
	v_mov_b32_e32 v4, v220
	v_mov_b32_e32 v5, v221
	s_nop 0
	v_cvt_pk_bf16_f32 v6, v4, v5
	ds_write_b16 v142, v6 offset:544
	ds_write_b16_d16_hi v142, v6 offset:672
	s_nop 0
	s_nop 0
	s_waitcnt lgkmcnt(15)
	v_fma_f32 v222, v66, v4, v222
	v_fma_f32 v223, v67, v5, v223
	v_fma_f32 v222, -v69, v5, v222
	v_fma_f32 v223, v68, v4, v223
	v_mov_b32_e32 v4, v222
	v_mov_b32_e32 v5, v223
	s_nop 0
	v_cvt_pk_bf16_f32 v6, v4, v5
	ds_write_b16 v142, v6 offset:816
	ds_write_b16_d16_hi v142, v6 offset:944
	s_nop 0
	s_nop 0
	s_waitcnt lgkmcnt(15)
	v_fma_f32 v224, v66, v4, v224
	v_fma_f32 v225, v67, v5, v225
	v_fma_f32 v224, -v69, v5, v224
	v_fma_f32 v225, v68, v4, v225
	v_mov_b32_e32 v4, v224
	v_mov_b32_e32 v5, v225
	s_nop 0
	v_cvt_pk_bf16_f32 v6, v4, v5
	ds_write_b16 v142, v6 offset:1088
	ds_write_b16_d16_hi v142, v6 offset:1216
	s_nop 0
	s_nop 0
	s_waitcnt lgkmcnt(15)
	v_fma_f32 v226, v66, v4, v226
	v_fma_f32 v227, v67, v5, v227
	v_fma_f32 v226, -v69, v5, v226
	v_fma_f32 v227, v68, v4, v227
	v_mov_b32_e32 v4, v226
	v_mov_b32_e32 v5, v227
	s_nop 0
	v_cvt_pk_bf16_f32 v6, v4, v5
	ds_write_b16 v142, v6 offset:1360
	ds_write_b16_d16_hi v142, v6 offset:1488
	s_nop 0
	s_nop 0
	s_waitcnt lgkmcnt(15)
	v_fma_f32 v228, v66, v4, v228
	v_fma_f32 v229, v67, v5, v229
	v_fma_f32 v228, -v69, v5, v228
	v_fma_f32 v229, v68, v4, v229
	v_mov_b32_e32 v4, v228
	v_mov_b32_e32 v5, v229
	s_nop 0
	v_cvt_pk_bf16_f32 v6, v4, v5
	ds_write_b16 v142, v6 offset:1632
	ds_write_b16_d16_hi v142, v6 offset:1760
	s_nop 0
	s_nop 0
	s_waitcnt lgkmcnt(15)
	v_fma_f32 v230, v66, v4, v230
	v_fma_f32 v231, v67, v5, v231
	v_fma_f32 v230, -v69, v5, v230
	v_fma_f32 v231, v68, v4, v231
	v_mov_b32_e32 v4, v230
	v_mov_b32_e32 v5, v231
	s_nop 0
	v_cvt_pk_bf16_f32 v6, v4, v5
	ds_write_b16 v142, v6 offset:1904
	ds_write_b16_d16_hi v142, v6 offset:2032
	s_nop 0
	s_nop 0
	s_waitcnt lgkmcnt(15)
	v_fma_f32 v232, v66, v4, v232
	v_fma_f32 v233, v67, v5, v233
	v_fma_f32 v232, -v69, v5, v232
	v_fma_f32 v233, v68, v4, v233
	v_mov_b32_e32 v4, v232
	v_mov_b32_e32 v5, v233
	s_nop 0
	v_cvt_pk_bf16_f32 v6, v4, v5
	ds_write_b16 v142, v6 offset:2176
	ds_write_b16_d16_hi v142, v6 offset:2304
	s_nop 0
	s_nop 0
	s_waitcnt lgkmcnt(15)
	v_fma_f32 v234, v66, v4, v234
	v_fma_f32 v235, v67, v5, v235
	v_fma_f32 v234, -v69, v5, v234
	v_fma_f32 v235, v68, v4, v235
	v_mov_b32_e32 v4, v234
	v_mov_b32_e32 v5, v235
	s_nop 0
	v_cvt_pk_bf16_f32 v6, v4, v5
	ds_write_b16 v142, v6 offset:2448
	ds_write_b16_d16_hi v142, v6 offset:2576
	s_nop 0
	s_nop 0
	s_waitcnt lgkmcnt(15)
	v_fma_f32 v236, v66, v4, v236
	v_fma_f32 v237, v67, v5, v237
	v_fma_f32 v236, -v69, v5, v236
	v_fma_f32 v237, v68, v4, v237
	v_mov_b32_e32 v4, v236
	v_mov_b32_e32 v5, v237
	s_nop 0
	v_cvt_pk_bf16_f32 v6, v4, v5
	ds_write_b16 v142, v6 offset:2720
	ds_write_b16_d16_hi v142, v6 offset:2848
	s_nop 0
	s_nop 0
	s_waitcnt lgkmcnt(15)
	v_fma_f32 v238, v66, v4, v238
	v_fma_f32 v239, v67, v5, v239
	v_fma_f32 v238, -v69, v5, v238
	v_fma_f32 v239, v68, v4, v239
	v_mov_b32_e32 v4, v238
	v_mov_b32_e32 v5, v239
	s_nop 0
	v_cvt_pk_bf16_f32 v6, v4, v5
	ds_write_b16 v142, v6 offset:2992
	ds_write_b16_d16_hi v142, v6 offset:3120
	s_nop 0
	s_nop 0
	s_waitcnt lgkmcnt(15)
	v_fma_f32 v240, v66, v4, v240
	v_fma_f32 v241, v67, v5, v241
	v_fma_f32 v240, -v69, v5, v240
	v_fma_f32 v241, v68, v4, v241
	v_mov_b32_e32 v4, v240
	v_mov_b32_e32 v5, v241
	s_nop 0
	v_cvt_pk_bf16_f32 v6, v4, v5
	ds_write_b16 v142, v6 offset:3264
	ds_write_b16_d16_hi v142, v6 offset:3392
	s_nop 0
	s_nop 0
	s_waitcnt lgkmcnt(15)
	v_fma_f32 v242, v66, v4, v242
	v_fma_f32 v243, v67, v5, v243
	v_fma_f32 v242, -v69, v5, v242
	v_fma_f32 v243, v68, v4, v243
	v_mov_b32_e32 v4, v242
	v_mov_b32_e32 v5, v243
	s_nop 0
	v_cvt_pk_bf16_f32 v6, v4, v5
	ds_write_b16 v142, v6 offset:3536
	ds_write_b16_d16_hi v142, v6 offset:3664
	s_nop 0
	s_nop 0
	s_waitcnt lgkmcnt(15)
	v_fma_f32 v244, v66, v4, v244
	v_fma_f32 v245, v67, v5, v245
	v_fma_f32 v244, -v69, v5, v244
	v_fma_f32 v245, v68, v4, v245
	v_mov_b32_e32 v4, v244
	v_mov_b32_e32 v5, v245
	s_nop 0
	v_cvt_pk_bf16_f32 v6, v4, v5
	ds_write_b16 v142, v6 offset:3808
	ds_write_b16_d16_hi v142, v6 offset:3936
	s_nop 0
	s_nop 0
	s_waitcnt lgkmcnt(15)
	v_fma_f32 v246, v66, v4, v246
	v_fma_f32 v247, v67, v5, v247
	v_fma_f32 v246, -v69, v5, v246
	v_fma_f32 v247, v68, v4, v247
	v_mov_b32_e32 v128, v246
	v_mov_b32_e32 v129, v247
	s_nop 0
	v_cvt_pk_bf16_f32 v4, v128, v129
	ds_write_b16 v142, v4 offset:4080
	ds_write_b16_d16_hi v142, v4 offset:4208
	s_waitcnt lgkmcnt(0)
	ds_read_b128 v[4:7], v144
	ds_read_b128 v[8:11], v144 offset:64
	s_waitcnt lgkmcnt(1)
	v_mfma_f32_16x16x32_bf16 v[4:7], v[4:7], v[50:53], 0
	ds_read_b128 v[12:15], v144 offset:128
	s_waitcnt lgkmcnt(1)
	v_mfma_f32_16x16x32_bf16 v[4:7], v[8:11], v[46:49], v[4:7]
	ds_read_b128 v[8:11], v144 offset:192
	s_waitcnt lgkmcnt(1)
	v_mfma_f32_16x16x32_bf16 v[4:7], v[12:15], v[42:45], v[4:7]
	s_waitcnt lgkmcnt(0)
	v_mfma_f32_16x16x32_bf16 v[4:7], v[8:11], v[38:41], v[4:7]
	s_nop 7
	v_fma_f32 v4, v148, v149, v4
	v_mul_f32_e32 v8, 0x3d372713, v4
	v_mul_f32_e32 v8, v4, v8
	v_fma_f32 v5, v146, v149, v5
	v_fma_f32 v8, v4, v8, v4
	v_mul_f32_e32 v9, 0x3d372713, v5
	v_mul_f32_e32 v8, 0xbfcc422a, v8
	v_mul_f32_e32 v9, v5, v9
	v_mul_f32_e32 v8, 0x3fb8aa3b, v8
	v_fma_f32 v9, v5, v9, v5
	v_exp_f32_e32 v8, v8
	v_mul_f32_e32 v9, 0xbfcc422a, v9
	v_mul_f32_e32 v9, 0x3fb8aa3b, v9
	v_exp_f32_e32 v9, v9
	v_add_f32_e32 v8, 1.0, v8
	v_rcp_f32_e32 v8, v8
	v_fmac_f32_e32 v7, v131, v149
	v_add_f32_e32 v9, 1.0, v9
	v_rcp_f32_e32 v9, v9
	v_mul_f32_e32 v4, v4, v8
	v_cvt_pk_bf16_f32 v4, v4, v20
	ds_write_b16 v130, v4 offset:25344
	v_mul_f32_e32 v4, v5, v9
	v_fma_f32 v5, v147, v149, v6
	v_mul_f32_e32 v6, 0x3d372713, v5
	v_mul_f32_e32 v8, 0x3d372713, v7
	v_mul_f32_e32 v6, v5, v6
	v_mul_f32_e32 v8, v7, v8
	v_fma_f32 v6, v5, v6, v5
	v_fma_f32 v8, v7, v8, v7
	v_mul_f32_e32 v6, 0xbfcc422a, v6
	v_mul_f32_e32 v8, 0xbfcc422a, v8
	v_mul_f32_e32 v6, 0x3fb8aa3b, v6
	v_mul_f32_e32 v8, 0x3fb8aa3b, v8
	v_exp_f32_e32 v6, v6
	v_exp_f32_e32 v8, v8
	v_cvt_pk_bf16_f32 v4, v4, v20
	ds_write_b16 v130, v4 offset:25872
	v_add_f32_e32 v6, 1.0, v6
	v_add_f32_e32 v4, 1.0, v8
	v_rcp_f32_e32 v6, v6
	v_rcp_f32_e32 v4, v4
	v_mul_f32_e32 v5, v5, v6
	v_mul_f32_e32 v4, v7, v4
	v_cvt_pk_bf16_f32 v5, v5, v20
	ds_write_b16 v130, v5 offset:26400
	v_cvt_pk_bf16_f32 v4, v4, v20
	ds_write_b16 v130, v4 offset:26928
	s_waitcnt lgkmcnt(0)
	s_andn2_b64 vcc, exec, s[46:47]
	s_cbranch_vccnz .LBB0_484
	s_branch .LBB0_524

.LBB0_522:
	v_mfma_f32_16x16x32_bf16 v[62:65], v[58:61], v[30:33], 0
	v_mfma_f32_16x16x32_bf16 v[182:185], v[58:61], v[34:37], 0
	s_nop 7
	ds_write2_b32 v140, v62, v182 offset1:16
	ds_write2_b32 v140, v63, v183 offset0:132 offset1:148
	ds_write2_b32 v165, v64, v184 offset0:8 offset1:24
	ds_write2_b32 v165, v65, v185 offset0:140 offset1:156
	v_mfma_f32_16x16x32_bf16 v[62:65], v[58:61], v[22:25], 0
	v_mfma_f32_16x16x32_bf16 v[182:185], v[58:61], v[26:29], 0
	s_nop 7
	ds_write2_b32 v140, v62, v182 offset0:32 offset1:48
	ds_write2_b32 v140, v63, v183 offset0:164 offset1:180
	ds_write2_b32 v165, v64, v184 offset0:40 offset1:56
	ds_write2_b32 v165, v65, v185 offset0:172 offset1:188
	v_mfma_f32_16x16x32_bf16 v[62:65], v[58:61], v[16:19], 0
	v_mfma_f32_16x16x32_bf16 v[182:185], v[58:61], v[12:15], 0
	s_nop 7
	ds_write2_b32 v140, v62, v182 offset0:64 offset1:80
	ds_write2_b32 v140, v63, v183 offset0:196 offset1:212
	ds_write2_b32 v165, v64, v184 offset0:72 offset1:88
	ds_write2_b32 v165, v65, v185 offset0:204 offset1:220
	v_mfma_f32_16x16x32_bf16 v[62:65], v[58:61], v[8:11], 0
	v_mfma_f32_16x16x32_bf16 v[58:61], v[58:61], v[4:7], 0
	s_nop 7
	ds_write2_b32 v140, v62, v58 offset0:96 offset1:112
	ds_write2_b32 v140, v63, v59 offset0:228 offset1:244
	ds_write2_b32 v165, v64, v60 offset0:104 offset1:120
	ds_write2_b32 v165, v65, v61 offset0:236 offset1:252
	s_waitcnt lgkmcnt(0)
	ds_read2st64_b32 v[216:217], v141 offset1:1
	v_add_u32_e32 v207, 16, v141
	ds_read2st64_b32 v[218:219], v207 offset0:2 offset1:3
	v_add_u32_e32 v207, 32, v141
	ds_read2st64_b32 v[220:221], v207 offset0:4 offset1:5
	v_add_u32_e32 v207, 48, v141
	ds_read2st64_b32 v[222:223], v207 offset0:6 offset1:7
	v_add_u32_e32 v207, 64, v141
	ds_read2st64_b32 v[224:225], v207 offset0:8 offset1:9
	v_add_u32_e32 v207, 80, v141
	ds_read2st64_b32 v[226:227], v207 offset0:10 offset1:11
	v_add_u32_e32 v207, 96, v141
	ds_read2st64_b32 v[228:229], v207 offset0:12 offset1:13
	v_add_u32_e32 v207, 112, v141
	ds_read2st64_b32 v[230:231], v207 offset0:14 offset1:15
	v_add_u32_e32 v207, 128, v141
	ds_read2st64_b32 v[232:233], v207 offset0:16 offset1:17
	v_add_u32_e32 v207, 144, v141
	ds_read2st64_b32 v[234:235], v207 offset0:18 offset1:19
	v_add_u32_e32 v207, 160, v141
	ds_read2st64_b32 v[236:237], v207 offset0:20 offset1:21
	v_add_u32_e32 v207, 176, v141
	ds_read2st64_b32 v[238:239], v207 offset0:22 offset1:23
	v_add_u32_e32 v207, 192, v141
	ds_read2st64_b32 v[240:241], v207 offset0:24 offset1:25
	v_add_u32_e32 v207, 208, v141
	ds_read2st64_b32 v[242:243], v207 offset0:26 offset1:27
	v_add_u32_e32 v207, 224, v141
	ds_read2st64_b32 v[244:245], v207 offset0:28 offset1:29
	v_add_u32_e32 v207, 240, v141
	ds_read2st64_b32 v[246:247], v207 offset0:30 offset1:31
	s_nop 0
	s_nop 0
	s_waitcnt lgkmcnt(15)
	v_fma_f32 v216, v66, v128, v216
	v_fma_f32 v217, v67, v129, v217
	v_fma_f32 v216, -v69, v129, v216
	v_fma_f32 v217, v68, v128, v217
	v_mov_b32_e32 v58, v216
	v_mov_b32_e32 v59, v217
	s_nop 0
	v_cvt_pk_bf16_f32 v60, v58, v59
	ds_write_b16 v142, v60
	ds_write_b16_d16_hi v142, v60 offset:128
	s_nop 0
	s_nop 0
	s_waitcnt lgkmcnt(15)
	v_fma_f32 v218, v66, v58, v218
	v_fma_f32 v219, v67, v59, v219
	v_fma_f32 v218, -v69, v59, v218
	v_fma_f32 v219, v68, v58, v219
	v_mov_b32_e32 v58, v218
	v_mov_b32_e32 v59, v219
	s_nop 0
	v_cvt_pk_bf16_f32 v60, v58, v59
	ds_write_b16 v142, v60 offset:272
	ds_write_b16_d16_hi v142, v60 offset:400
	s_nop 0
	s_nop 0
	s_waitcnt lgkmcnt(15)
	v_fma_f32 v220, v66, v58, v220
	v_fma_f32 v221, v67, v59, v221
	v_fma_f32 v220, -v69, v59, v220
	v_fma_f32 v221, v68, v58, v221
	v_mov_b32_e32 v58, v220
	v_mov_b32_e32 v59, v221
	s_nop 0
	v_cvt_pk_bf16_f32 v60, v58, v59
	ds_write_b16 v142, v60 offset:544
	ds_write_b16_d16_hi v142, v60 offset:672
	s_nop 0
	s_nop 0
	s_waitcnt lgkmcnt(15)
	v_fma_f32 v222, v66, v58, v222
	v_fma_f32 v223, v67, v59, v223
	v_fma_f32 v222, -v69, v59, v222
	v_fma_f32 v223, v68, v58, v223
	v_mov_b32_e32 v58, v222
	v_mov_b32_e32 v59, v223
	s_nop 0
	v_cvt_pk_bf16_f32 v60, v58, v59
	ds_write_b16 v142, v60 offset:816
	ds_write_b16_d16_hi v142, v60 offset:944
	s_nop 0
	s_nop 0
	s_waitcnt lgkmcnt(15)
	v_fma_f32 v224, v66, v58, v224
	v_fma_f32 v225, v67, v59, v225
	v_fma_f32 v224, -v69, v59, v224
	v_fma_f32 v225, v68, v58, v225
	v_mov_b32_e32 v58, v224
	v_mov_b32_e32 v59, v225
	s_nop 0
	v_cvt_pk_bf16_f32 v60, v58, v59
	ds_write_b16 v142, v60 offset:1088
	ds_write_b16_d16_hi v142, v60 offset:1216
	s_nop 0
	s_nop 0
	s_waitcnt lgkmcnt(15)
	v_fma_f32 v226, v66, v58, v226
	v_fma_f32 v227, v67, v59, v227
	v_fma_f32 v226, -v69, v59, v226
	v_fma_f32 v227, v68, v58, v227
	v_mov_b32_e32 v58, v226
	v_mov_b32_e32 v59, v227
	s_nop 0
	v_cvt_pk_bf16_f32 v60, v58, v59
	ds_write_b16 v142, v60 offset:1360
	ds_write_b16_d16_hi v142, v60 offset:1488
	s_nop 0
	s_nop 0
	s_waitcnt lgkmcnt(15)
	v_fma_f32 v228, v66, v58, v228
	v_fma_f32 v229, v67, v59, v229
	v_fma_f32 v228, -v69, v59, v228
	v_fma_f32 v229, v68, v58, v229
	v_mov_b32_e32 v58, v228
	v_mov_b32_e32 v59, v229
	s_nop 0
	v_cvt_pk_bf16_f32 v60, v58, v59
	ds_write_b16 v142, v60 offset:1632
	ds_write_b16_d16_hi v142, v60 offset:1760
	s_nop 0
	s_nop 0
	s_waitcnt lgkmcnt(15)
	v_fma_f32 v230, v66, v58, v230
	v_fma_f32 v231, v67, v59, v231
	v_fma_f32 v230, -v69, v59, v230
	v_fma_f32 v231, v68, v58, v231
	v_mov_b32_e32 v58, v230
	v_mov_b32_e32 v59, v231
	s_nop 0
	v_cvt_pk_bf16_f32 v60, v58, v59
	ds_write_b16 v142, v60 offset:1904
	ds_write_b16_d16_hi v142, v60 offset:2032
	s_nop 0
	s_nop 0
	s_waitcnt lgkmcnt(15)
	v_fma_f32 v232, v66, v58, v232
	v_fma_f32 v233, v67, v59, v233
	v_fma_f32 v232, -v69, v59, v232
	v_fma_f32 v233, v68, v58, v233
	v_mov_b32_e32 v58, v232
	v_mov_b32_e32 v59, v233
	s_nop 0
	v_cvt_pk_bf16_f32 v60, v58, v59
	ds_write_b16 v142, v60 offset:2176
	ds_write_b16_d16_hi v142, v60 offset:2304
	s_nop 0
	s_nop 0
	s_waitcnt lgkmcnt(15)
	v_fma_f32 v234, v66, v58, v234
	v_fma_f32 v235, v67, v59, v235
	v_fma_f32 v234, -v69, v59, v234
	v_fma_f32 v235, v68, v58, v235
	v_mov_b32_e32 v58, v234
	v_mov_b32_e32 v59, v235
	s_nop 0
	v_cvt_pk_bf16_f32 v60, v58, v59
	ds_write_b16 v142, v60 offset:2448
	ds_write_b16_d16_hi v142, v60 offset:2576
	s_nop 0
	s_nop 0
	s_waitcnt lgkmcnt(15)
	v_fma_f32 v236, v66, v58, v236
	v_fma_f32 v237, v67, v59, v237
	v_fma_f32 v236, -v69, v59, v236
	v_fma_f32 v237, v68, v58, v237
	v_mov_b32_e32 v58, v236
	v_mov_b32_e32 v59, v237
	s_nop 0
	v_cvt_pk_bf16_f32 v60, v58, v59
	ds_write_b16 v142, v60 offset:2720
	ds_write_b16_d16_hi v142, v60 offset:2848
	s_nop 0
	s_nop 0
	s_waitcnt lgkmcnt(15)
	v_fma_f32 v238, v66, v58, v238
	v_fma_f32 v239, v67, v59, v239
	v_fma_f32 v238, -v69, v59, v238
	v_fma_f32 v239, v68, v58, v239
	v_mov_b32_e32 v58, v238
	v_mov_b32_e32 v59, v239
	s_nop 0
	v_cvt_pk_bf16_f32 v60, v58, v59
	ds_write_b16 v142, v60 offset:2992
	ds_write_b16_d16_hi v142, v60 offset:3120
	s_nop 0
	s_nop 0
	s_waitcnt lgkmcnt(15)
	v_fma_f32 v240, v66, v58, v240
	v_fma_f32 v241, v67, v59, v241
	v_fma_f32 v240, -v69, v59, v240
	v_fma_f32 v241, v68, v58, v241
	v_mov_b32_e32 v58, v240
	v_mov_b32_e32 v59, v241
	s_nop 0
	v_cvt_pk_bf16_f32 v60, v58, v59
	ds_write_b16 v142, v60 offset:3264
	ds_write_b16_d16_hi v142, v60 offset:3392
	s_nop 0
	s_nop 0
	s_waitcnt lgkmcnt(15)
	v_fma_f32 v242, v66, v58, v242
	v_fma_f32 v243, v67, v59, v243
	v_fma_f32 v242, -v69, v59, v242
	v_fma_f32 v243, v68, v58, v243
	v_mov_b32_e32 v58, v242
	v_mov_b32_e32 v59, v243
	s_nop 0
	v_cvt_pk_bf16_f32 v60, v58, v59
	ds_write_b16 v142, v60 offset:3536
	ds_write_b16_d16_hi v142, v60 offset:3664
	s_nop 0
	s_nop 0
	s_waitcnt lgkmcnt(15)
	v_fma_f32 v244, v66, v58, v244
	v_fma_f32 v245, v67, v59, v245
	v_fma_f32 v244, -v69, v59, v244
	v_fma_f32 v245, v68, v58, v245
	v_mov_b32_e32 v58, v244
	v_mov_b32_e32 v59, v245
	s_nop 0
	v_cvt_pk_bf16_f32 v60, v58, v59
	ds_write_b16 v142, v60 offset:3808
	ds_write_b16_d16_hi v142, v60 offset:3936
	s_nop 0
	s_nop 0
	s_waitcnt lgkmcnt(15)
	v_fma_f32 v246, v66, v58, v246
	v_fma_f32 v247, v67, v59, v247
	v_fma_f32 v246, -v69, v59, v246
	v_fma_f32 v247, v68, v58, v247
	v_mov_b32_e32 v128, v246
	v_mov_b32_e32 v129, v247
	s_nop 0
	v_cvt_pk_bf16_f32 v58, v128, v129
	ds_write_b16 v142, v58 offset:4080
	ds_write_b16_d16_hi v142, v58 offset:4208
	s_waitcnt lgkmcnt(0)
	ds_read_b128 v[58:61], v144
	ds_read_b128 v[62:65], v144 offset:64
	s_waitcnt lgkmcnt(1)
	v_mfma_f32_16x16x32_bf16 v[58:61], v[58:61], v[50:53], 0
	s_waitcnt lgkmcnt(0)
	v_mfma_f32_16x16x32_bf16 v[58:61], v[62:65], v[46:49], v[58:61]
	ds_read_b128 v[62:65], v144 offset:128
	s_waitcnt lgkmcnt(0)
	v_mfma_f32_16x16x32_bf16 v[58:61], v[62:65], v[42:45], v[58:61]
	ds_read_b128 v[62:65], v144 offset:192
	s_waitcnt lgkmcnt(0)
	v_mfma_f32_16x16x32_bf16 v[58:61], v[62:65], v[38:41], v[58:61]
	s_nop 7
	v_fma_f32 v58, v166, v149, v58
	v_mul_f32_e32 v62, 0x3d372713, v58
	v_mul_f32_e32 v62, v58, v62
	v_fma_f32 v62, v58, v62, v58
	v_mul_f32_e32 v62, 0xbfcc422a, v62
	v_mul_f32_e32 v62, 0x3fb8aa3b, v62
	v_exp_f32_e32 v62, v62
	v_fmac_f32_e32 v61, v162, v149
	v_add_f32_e32 v62, 1.0, v62
	v_rcp_f32_e32 v62, v62
	s_nop 0
	v_mul_f32_e32 v58, v58, v62
	v_cvt_pk_bf16_f32 v58, v58, v20
	ds_write_b16 v130, v58 offset:16896
	v_fma_f32 v58, v164, v149, v59
	v_mul_f32_e32 v59, 0x3d372713, v58
	v_mul_f32_e32 v59, v58, v59
	v_fma_f32 v59, v58, v59, v58
	v_mul_f32_e32 v59, 0xbfcc422a, v59
	v_mul_f32_e32 v59, 0x3fb8aa3b, v59
	v_exp_f32_e32 v59, v59
	s_nop 0
	v_add_f32_e32 v59, 1.0, v59
	v_rcp_f32_e32 v59, v59
	s_nop 0
	v_mul_f32_e32 v58, v58, v59
	v_cvt_pk_bf16_f32 v58, v58, v20
	ds_write_b16 v130, v58 offset:17424
	v_fma_f32 v58, v163, v149, v60
	v_mul_f32_e32 v59, 0x3d372713, v58
	v_mul_f32_e32 v59, v58, v59
	v_fma_f32 v59, v58, v59, v58
	v_mul_f32_e32 v59, 0xbfcc422a, v59
	v_mul_f32_e32 v59, 0x3fb8aa3b, v59
	v_exp_f32_e32 v59, v59
	s_nop 0
	v_add_f32_e32 v59, 1.0, v59
	v_rcp_f32_e32 v59, v59
	s_nop 0
	v_mul_f32_e32 v58, v58, v59
	v_cvt_pk_bf16_f32 v58, v58, v20
	ds_write_b16 v130, v58 offset:17952
	v_mul_f32_e32 v58, 0x3d372713, v61
	v_mul_f32_e32 v58, v61, v58
	v_fma_f32 v58, v61, v58, v61
	v_mul_f32_e32 v58, 0xbfcc422a, v58
	v_mul_f32_e32 v58, 0x3fb8aa3b, v58
	v_exp_f32_e32 v58, v58
	s_nop 0
	v_add_f32_e32 v58, 1.0, v58
	v_rcp_f32_e32 v58, v58
	s_nop 0
	v_mul_f32_e32 v58, v61, v58
	v_cvt_pk_bf16_f32 v58, v58, v20
	ds_write_b16 v130, v58 offset:18480
	s_waitcnt lgkmcnt(0)
	s_and_b64 vcc, exec, s[38:39]
	s_cbranch_vccz .LBB0_520
